# phase 3: static s_setprio 1 for waves 0-3 instead (the other half), reset at phase end
# speedup vs baseline: 1.0023x; 1.0010x over previous
.LBB0_624:
	v_readfirstlane_b32 s98, v224
	s_nop 3
	s_cmp_lt_u32 s98, 0x100
	s_cbranch_scc0 .Lmy_p3_noprio
	s_setprio 1
